# main-loop LDS-DMA loads switched to SGPR-base plus 32-bit VGPR offset form (removes 16 v_lshl_add_u64 per iteration)
# speedup vs baseline: 1.0015x; 1.0015x over previous
; #define PG8_STAGE(bufoff, gbase, voff) do { _Pragma("unroll") for (int _i = 0; _i < 2; ++_i) \
;         __builtin_amdgcn_global_load_lds((const unsigned*)((const char*)(gbase) + (voff)[_i]), (LAS unsigned*)(lds + (bufoff) + ldsw + _i * 8192), 16, 0, 0); } while (0)
; #define PG8_WAIT_V(n) asm volatile("s_waitcnt vmcnt(" #n ")" ::: "memory")
; #define PG8_BAR __builtin_amdgcn_s_barrier()
; __device__ __forceinline__ void gemm_phase(LAS unsigned char* lds, const GemmD g, const Sched& S, const Epi& E) {
;     ...
;     for (int i = 0; i < 2; ++i) { int R, C; stage_rc(tid * 16 + i * 8192, R, C); const int Rb = (R & ~31) + perm32(R & 31);
;         voffA[i] = (unsigned)(R * g.lda + C) * 2u; voffB[i] = (unsigned)(Rb * g.ldb + C) * 2u; }
;     const size_t kstep = (size_t)(BK * 2);
;     const size_t hstepA = (size_t)HALF * g.lda * 2, tstepA = 2 * hstepA;
;     const size_t hstepB = (size_t)HALF * g.ldb * 2, tstepB = 2 * hstepB;
;     const unsigned ldsw = (unsigned)wid * 1024u;
;     ...
;     const char* cA = (const char*)g.A + (size_t)cur.pm * tstepA; const char* cB = (const char*)g.Bt + (size_t)cur.pn * tstepB;
;     PG8_STAGE(PG8_SB(0, 0), cB, voffB); PG8_STAGE(PG8_SB(0, 1), cB + hstepB, voffB); PG8_STAGE(PG8_SA(0, 0), cA, voffA); PG8_STAGE(PG8_SA(0, 1), cA + hstepA, voffA);
;     if (wr == 1) PG8_BAR;
;     PG8_WAIT_V(2); PG8_BAR;
;     PG8_STAGE(PG8_SB(1, 0), cB + kstep, voffB); PG8_STAGE(PG8_SA(1, 0), cA + kstep, voffA); PG8_STAGE(PG8_SB(1, 1), cB + hstepB + kstep, voffB);
;     PG8_WAIT_V(6); PG8_BAR;
.LBB0_199:
	s_waitcnt vmcnt(3)
	v_bfe_i32 v3, v19, 27, 1
	s_waitcnt lgkmcnt(0)
	v_lshlrev_b32_e32 v2, 4, v19
	v_lshrrev_b32_e32 v3, 22, v3
	v_add_u32_e32 v3, v2, v3
	v_and_b32_e32 v3, 0xfffffc00, v3
	v_ashrrev_i32_e32 v0, 31, v19
	v_sub_u32_e32 v3, v2, v3
	v_lshrrev_b32_e32 v0, 26, v0
	v_lshrrev_b32_e32 v4, 4, v3
	v_add_u32_e32 v0, v19, v0
	v_bitop3_b32 v4, v4, v3, 32 bitop3:0x6c
	v_ashrrev_i32_e32 v3, 31, v3
	v_ashrrev_i32_e32 v0, 6, v0
	v_lshrrev_b32_e32 v3, 26, v3
	v_lshlrev_b32_e32 v5, 3, v0
	v_add_u32_e32 v3, v4, v3
	v_and_b32_e32 v5, -16, v5
	v_ashrrev_i32_e32 v3, 6, v3
	v_add_u32_e32 v5, v3, v5
	s_waitcnt vmcnt(2)
	v_mul_i32_i24_e32 v6, 64, v3
	v_sub_u32_e32 v4, v4, v6
	v_lshlrev_b32_e32 v6, 1, v5
	v_lshrrev_b32_e32 v7, 2, v5
	v_and_b32_e32 v3, 3, v3
	s_mov_b32 s7, 0x7fffffe0
	v_lshlrev_b32_e32 v0, 5, v0
	v_ashrrev_i16_sdwa v4, v197, sext(v4) dst_sel:DWORD dst_unused:UNUSED_PAD src0_sel:DWORD src1_sel:BYTE_0
	v_and_b32_e32 v6, 24, v6
	v_and_b32_e32 v7, 4, v7
	v_and_or_b32 v3, v5, s7, v3
	v_and_b32_e32 v0, 32, v0
	v_bfe_i32 v14, v4, 0, 16
	v_or3_b32 v3, v3, v7, v6
	v_add_u32_e32 v4, v0, v14
	v_mul_lo_u32 v3, v3, s11
	v_add_u32_e32 v2, 0x2000, v2
	v_add_lshl_u32 v136, v3, v4, 1
	v_ashrrev_i32_e32 v3, 31, v2
	v_lshrrev_b32_e32 v3, 22, v3
	v_add_u32_e32 v3, v2, v3
	v_mul_lo_u32 v15, v5, s10
	v_ashrrev_i32_e32 v3, 10, v3
	v_add_lshl_u32 v134, v4, v15, 1
	v_mul_i32_i24_e32 v4, 0x400, v3
	v_sub_u32_e32 v2, v2, v4
	v_lshrrev_b32_e32 v4, 4, v2
	v_bitop3_b32 v2, v4, v2, 32 bitop3:0x6c
	v_ashrrev_i32_e32 v5, 31, v2
	s_lshl_b32 s94, s10, 8
	v_lshrrev_b32_e32 v5, 26, v5
	s_lshl_b64 s[14:15], s[94:95], 1
	s_ashr_i32 s8, s21, 31
	v_lshlrev_b32_e32 v4, 3, v3
	v_add_u32_e32 v5, v2, v5
	s_mul_i32 s8, s14, s8
	s_mul_hi_u32 s9, s14, s21
	v_and_b32_e32 v4, -16, v4
	v_ashrrev_i32_e32 v6, 6, v5
	s_add_i32 s8, s9, s8
	s_bfe_u32 s9, s10, 0x10017
	v_add_u32_e32 v4, v6, v4
	s_mul_i32 s9, s9, s21
	v_writelane_b32 v250, s14, 13
	v_and_b32_e32 v6, 3, v6
	v_mul_lo_u32 v18, v4, s10
	s_lshl_b32 s17, s11, 9
	s_add_i32 s10, s8, s9
	v_writelane_b32 v250, s15, 14
	s_ashr_i32 s8, s28, 31
	v_lshlrev_b32_e32 v3, 5, v3
	v_and_or_b32 v6, v4, s7, v6
	s_ashr_i32 s7, s16, 6
	s_mul_i32 s8, s17, s8
	s_mul_hi_u32 s9, s17, s28
	v_writelane_b32 v250, s17, 15
	s_ashr_i32 s6, s16, 8
	v_and_b32_e32 v16, 32, v3
	v_and_b32_e32 v3, 0xc0, v5
	s_lshl_b32 s29, s11, 8
	s_lshl_b32 s30, s7, 10
	s_mul_i32 s12, s14, s21
	s_add_i32 s9, s9, s8
	s_mul_i32 s8, s17, s28
	v_readlane_b32 s14, v250, 9
	v_sub_u32_e32 v2, v2, v3
	v_lshlrev_b32_e32 v3, 1, v4
	v_lshrrev_b32_e32 v5, 2, v4
	v_readlane_b32 s15, v250, 10
	s_add_u32 s26, s14, s8
	v_ashrrev_i16_sdwa v2, v197, sext(v2) dst_sel:DWORD dst_unused:UNUSED_PAD src0_sel:DWORD src1_sel:BYTE_0
	v_and_b32_e32 v3, 24, v3
	v_and_b32_e32 v5, 4, v5
	s_addc_u32 s27, s15, s9
	s_add_i32 s31, s30, 0
	v_bfe_i32 v17, v2, 0, 16
	v_or3_b32 v3, v6, v5, v3
	s_add_i32 m0, s31, 0x10000
	v_add_u32_e32 v2, v16, v17
	v_mul_lo_u32 v3, v3, s11
	global_load_lds_dwordx4 v136, s[26:27]
	s_add_i32 m0, s31, 0x12000
	v_add_lshl_u32 v140, v3, v2, 1
	s_add_u32 s8, s26, s29
	global_load_lds_dwordx4 v140, s[26:27]
	s_addc_u32 s9, s27, 0
	s_add_i32 m0, s31, 0x14000
	v_add_u32_e32 v253, s29, v136
	v_add_u32_e32 v254, s29, v140
	v_mov_b32_e32 v137, v1
	v_mov_b32_e32 v141, v1
	global_load_lds_dwordx4 v136, s[8:9]
	s_add_i32 m0, s31, 0x16000
	v_lshl_add_u64 v[6:7], s[8:9], 0, v[136:137]
	v_lshl_add_u64 v[8:9], s[8:9], 0, v[140:141]
	global_load_lds_dwordx4 v140, s[8:9]
	v_readlane_b32 s8, v250, 11
	v_readlane_b32 s9, v250, 12
	s_add_u32 s8, s8, s12
	s_addc_u32 s9, s9, s10
	s_add_i32 s14, s31, 0x2000
	s_mov_b32 m0, s31
	s_add_u32 s18, s8, s94
	v_add_lshl_u32 v138, v2, v18, 1
	global_load_lds_dwordx4 v134, s[8:9]
	s_mov_b32 m0, s14
	s_addc_u32 s19, s9, 0
	s_add_i32 s15, s31, 0x4000
	global_load_lds_dwordx4 v138, s[8:9]
	s_mov_b32 m0, s15
	s_add_i32 s10, s31, 0x6000
	global_load_lds_dwordx4 v134, s[18:19]
	s_mov_b32 m0, s10
	s_cmp_eq_u32 s6, 1
	global_load_lds_dwordx4 v138, s[18:19]
	v_mov_b32_e32 v135, v1
	v_mov_b32_e32 v139, v1
	s_cselect_b64 s[18:19], -1, 0
	v_lshl_add_u64 v[2:3], s[26:27], 0, v[136:137]
	v_lshl_add_u64 v[4:5], s[26:27], 0, v[140:141]
	s_waitcnt vmcnt(0)
	v_lshl_add_u64 v[10:11], s[8:9], 0, v[134:135]
	v_lshl_add_u64 v[12:13], s[8:9], 0, v[138:139]
	v_writelane_b32 v250, s18, 17
	s_cmp_lg_u32 s6, 1
	s_nop 0
	v_writelane_b32 v250, s19, 18
	s_cbranch_scc1 .LBB0_201
	s_barrier

; #define PG8_STAGE(bufoff, gbase, voff) do { _Pragma("unroll") for (int _i = 0; _i < 2; ++_i) \
;         __builtin_amdgcn_global_load_lds((const unsigned*)((const char*)(gbase) + (voff)[_i]), (LAS unsigned*)(lds + (bufoff) + ldsw + _i * 8192), 16, 0, 0); } while (0)
; #define PG8_LDA(dst, b, h) do { _Pragma("unroll") for (int m = 0; m < 4; ++m) _Pragma("unroll") for (int k = 0; k < 2; ++k) dst[m][k] = *(const LAS bf16x8*)(lds + PG8_SA(b, h) + aoff + m * 2048 + k * 1024); } while (0)
; #define PG8_LDB(dst, b, h) do { _Pragma("unroll") for (int n = 0; n < 2; ++n) _Pragma("unroll") for (int k = 0; k < 2; ++k) dst[n][k] = *(const LAS bf16x8*)(lds + PG8_SB(b, h) + boff + n * 2048 + k * 1024); } while (0)
; #define PG8_MMA(ai, bj, At, Bt) do { __builtin_amdgcn_s_setprio(1); _Pragma("unroll") for (int m = 0; m < 4; ++m) _Pragma("unroll") for (int n = 0; n < 2; ++n) _Pragma("unroll") for (int k = 0; k < 2; ++k) \
;         acc[ai][bj][m][n] = __builtin_amdgcn_mfma_f32_16x16x32_bf16(Bt[n][k], At[m][k], acc[ai][bj][m][n], 0, 0, 0); __builtin_amdgcn_s_setprio(0); } while (0)
; #define PG8_WAIT_V(n) asm volatile("s_waitcnt vmcnt(" #n ")" ::: "memory")
; #define PG8_WAIT_L(n) asm volatile("s_waitcnt lgkmcnt(" #n ")" ::: "memory")
; #define PG8_BAR __builtin_amdgcn_s_barrier()
; #define PG8_SCHED __builtin_amdgcn_sched_barrier(0)
; __device__ __forceinline__ void gemm_phase(LAS unsigned char* lds, const GemmD g, const Sched& S, const Epi& E) {
;     ...
;         for (int t = 0; t < nt; t += 2) {
;             const bool last = (t == nt - 2);
;             const char* a1 = cA + (size_t)(t + 1) * kstep;
;             const char* a2 = last ? nA : cA + (size_t)(t + 2) * kstep; const char* b2 = last ? nB : cB + (size_t)(t + 2) * kstep;
;             const char* a3 = a2 + kstep; const char* b3 = b2 + kstep;
;             PG8_LDB(B0, 0, 0); PG8_LDB(B1, 0, 1); PG8_SCHED; PG8_LDA(At, 0, 0); PG8_STAGE(PG8_SA(1, 1), a1 + hstepA, voffA);
;             PG8_WAIT_V(8); PG8_WAIT_L(0); PG8_BAR; PG8_MMA(0, 0, At, B0); PG8_MMA(0, 1, At, B1); PG8_BAR; PG8_SCHED;
;             PG8_LDA(At, 0, 1); PG8_STAGE(PG8_SB(0, 0), b2, voffB); PG8_STAGE(PG8_SB(0, 1), b2 + hstepB, voffB); PG8_STAGE(PG8_SA(0, 0), a2, voffA);
;             PG8_WAIT_V(8); PG8_WAIT_L(0); PG8_BAR; PG8_MMA(1, 0, At, B0); PG8_MMA(1, 1, At, B1); PG8_BAR; PG8_SCHED;
.Lprio_done:
.LBB0_215:
	s_add_i32 s92, s26, 2
	s_add_u32 s93, s8, 0x80
	s_addc_u32 s27, s9, 0
	s_add_i32 s22, 0, 0x10000
	s_cmp_eq_u32 s11, s26
	s_cselect_b32 s27, s1, s27
	s_cselect_b32 s26, s0, s93
	v_add_u32_e32 v0, s22, v160
	s_cselect_b32 vcc_hi, s17, s35
	s_cselect_b32 vcc_lo, s16, s34
	s_add_i32 s23, 0, 0x14000
	ds_read_b128 v[130:133], v0
	ds_read_b128 v[146:149], v0 offset:1024
	ds_read_b128 v[150:153], v0 offset:2048
	ds_read_b128 v[154:157], v0 offset:3072
	v_add_u32_e32 v0, s23, v160
	ds_read_b128 v[162:165], v0
	ds_read_b128 v[166:169], v0 offset:1024
	ds_read_b128 v[170:173], v0 offset:2048
	ds_read_b128 v[174:177], v0 offset:3072
	s_add_i32 m0, s31, 0xc000
	ds_read_b128 v[182:185], v161
	ds_read_b128 v[186:189], v161 offset:1024
	ds_read_b128 v[190:193], v161 offset:2048
	ds_read_b128 v[216:219], v161 offset:3072
	ds_read_b128 v[220:223], v161 offset:4096
	ds_read_b128 v[224:227], v161 offset:5120
	ds_read_b128 v[228:231], v161 offset:6144
	ds_read_b128 v[236:239], v161 offset:7168
	global_load_lds_dwordx4 v142, s[8:9]
	s_add_i32 m0, s31, 0xe000
	s_nop 0
	global_load_lds_dwordx4 v144, s[8:9]
	s_waitcnt vmcnt(8)
	s_waitcnt lgkmcnt(0)
	s_barrier
	s_waitcnt lgkmcnt(0)
	v_mfma_f32_16x16x32_bf16 v[126:129], v[130:133], v[182:185], v[126:129]
	v_mfma_f32_16x16x32_bf16 v[122:125], v[150:153], v[182:185], v[122:125]
	v_mfma_f32_16x16x32_bf16 v[110:113], v[130:133], v[190:193], v[110:113]
	v_mfma_f32_16x16x32_bf16 v[106:109], v[150:153], v[190:193], v[106:109]
	v_mfma_f32_16x16x32_bf16 v[94:97], v[130:133], v[220:223], v[94:97]
	v_mfma_f32_16x16x32_bf16 v[90:93], v[150:153], v[220:223], v[90:93]
	v_mfma_f32_16x16x32_bf16 v[78:81], v[130:133], v[228:231], v[78:81]
	v_mfma_f32_16x16x32_bf16 v[74:77], v[150:153], v[228:231], v[74:77]
	v_mfma_f32_16x16x32_bf16 v[126:129], v[146:149], v[186:189], v[126:129]
	v_mfma_f32_16x16x32_bf16 v[122:125], v[154:157], v[186:189], v[122:125]
	v_mfma_f32_16x16x32_bf16 v[110:113], v[146:149], v[216:219], v[110:113]
	v_mfma_f32_16x16x32_bf16 v[106:109], v[154:157], v[216:219], v[106:109]
	v_mfma_f32_16x16x32_bf16 v[94:97], v[146:149], v[224:227], v[94:97]
	v_mfma_f32_16x16x32_bf16 v[90:93], v[154:157], v[224:227], v[90:93]
	v_mfma_f32_16x16x32_bf16 v[78:81], v[146:149], v[236:239], v[78:81]
	v_mfma_f32_16x16x32_bf16 v[74:77], v[154:157], v[236:239], v[74:77]
	v_mfma_f32_16x16x32_bf16 v[118:121], v[162:165], v[182:185], v[118:121]
	v_mfma_f32_16x16x32_bf16 v[114:117], v[170:173], v[182:185], v[114:117]
	v_mfma_f32_16x16x32_bf16 v[102:105], v[162:165], v[190:193], v[102:105]
	v_mfma_f32_16x16x32_bf16 v[98:101], v[170:173], v[190:193], v[98:101]
	v_mfma_f32_16x16x32_bf16 v[86:89], v[162:165], v[220:223], v[86:89]
	v_mfma_f32_16x16x32_bf16 v[82:85], v[170:173], v[220:223], v[82:85]
	v_mfma_f32_16x16x32_bf16 v[70:73], v[162:165], v[228:231], v[70:73]
	v_mfma_f32_16x16x32_bf16 v[66:69], v[170:173], v[228:231], v[66:69]
	v_mfma_f32_16x16x32_bf16 v[118:121], v[166:169], v[186:189], v[118:121]
	v_mfma_f32_16x16x32_bf16 v[114:117], v[174:177], v[186:189], v[114:117]
	v_mfma_f32_16x16x32_bf16 v[102:105], v[166:169], v[216:219], v[102:105]
	v_mfma_f32_16x16x32_bf16 v[98:101], v[174:177], v[216:219], v[98:101]
	v_mfma_f32_16x16x32_bf16 v[86:89], v[166:169], v[224:227], v[86:89]
	v_mfma_f32_16x16x32_bf16 v[82:85], v[174:177], v[224:227], v[82:85]
	v_mfma_f32_16x16x32_bf16 v[70:73], v[166:169], v[236:239], v[70:73]
	v_mfma_f32_16x16x32_bf16 v[66:69], v[174:177], v[236:239], v[66:69]
	s_barrier
	s_add_i32 s22, s22, s30
	s_mov_b32 m0, s22
	ds_read_b128 v[182:185], v161 offset:16384
	ds_read_b128 v[186:189], v161 offset:17408
	ds_read_b128 v[190:193], v161 offset:18432
	ds_read_b128 v[216:219], v161 offset:19456
	ds_read_b128 v[220:223], v161 offset:20480
	ds_read_b128 v[224:227], v161 offset:21504
	ds_read_b128 v[228:231], v161 offset:22528
	ds_read_b128 v[236:239], v161 offset:23552
	global_load_lds_dwordx4 v136, vcc
	s_add_i32 m0, s22, 0x2000
	s_add_i32 s22, s23, s30
	global_load_lds_dwordx4 v140, vcc
	s_mov_b32 m0, s22
	s_nop 0
	global_load_lds_dwordx4 v253, vcc
	s_add_i32 m0, s22, 0x2000
	s_nop 0
	global_load_lds_dwordx4 v254, vcc
	s_mov_b32 m0, s31
	s_nop 0
	global_load_lds_dwordx4 v134, s[26:27]
	s_mov_b32 m0, s14
	s_nop 0
	global_load_lds_dwordx4 v138, s[26:27]
	s_waitcnt vmcnt(8)
	s_waitcnt lgkmcnt(0)
	s_barrier
	s_waitcnt lgkmcnt(0)
	v_mfma_f32_16x16x32_bf16 v[62:65], v[130:133], v[182:185], v[62:65]
	v_mfma_f32_16x16x32_bf16 v[58:61], v[150:153], v[182:185], v[58:61]
	v_mfma_f32_16x16x32_bf16 v[46:49], v[130:133], v[190:193], v[46:49]
	v_mfma_f32_16x16x32_bf16 v[42:45], v[150:153], v[190:193], v[42:45]
	v_mfma_f32_16x16x32_bf16 v[30:33], v[130:133], v[220:223], v[30:33]
	v_mfma_f32_16x16x32_bf16 v[26:29], v[150:153], v[220:223], v[26:29]
	v_mfma_f32_16x16x32_bf16 v[14:17], v[130:133], v[228:231], v[14:17]
	v_mfma_f32_16x16x32_bf16 v[10:13], v[150:153], v[228:231], v[10:13]
	v_mfma_f32_16x16x32_bf16 v[62:65], v[146:149], v[186:189], v[62:65]
	v_mfma_f32_16x16x32_bf16 v[58:61], v[154:157], v[186:189], v[58:61]
	v_mfma_f32_16x16x32_bf16 v[46:49], v[146:149], v[216:219], v[46:49]
	v_mfma_f32_16x16x32_bf16 v[42:45], v[154:157], v[216:219], v[42:45]
	v_mfma_f32_16x16x32_bf16 v[30:33], v[146:149], v[224:227], v[30:33]
	v_mfma_f32_16x16x32_bf16 v[26:29], v[154:157], v[224:227], v[26:29]
	v_mfma_f32_16x16x32_bf16 v[14:17], v[146:149], v[236:239], v[14:17]
	v_mfma_f32_16x16x32_bf16 v[10:13], v[154:157], v[236:239], v[10:13]
	v_mfma_f32_16x16x32_bf16 v[54:57], v[162:165], v[182:185], v[54:57]
	v_mfma_f32_16x16x32_bf16 v[50:53], v[170:173], v[182:185], v[50:53]
	v_mfma_f32_16x16x32_bf16 v[38:41], v[162:165], v[190:193], v[38:41]
	v_mfma_f32_16x16x32_bf16 v[34:37], v[170:173], v[190:193], v[34:37]
	v_mfma_f32_16x16x32_bf16 v[22:25], v[162:165], v[220:223], v[22:25]
	v_mfma_f32_16x16x32_bf16 v[18:21], v[170:173], v[220:223], v[18:21]
	v_mfma_f32_16x16x32_bf16 v[6:9], v[162:165], v[228:231], v[6:9]
	v_mfma_f32_16x16x32_bf16 v[2:5], v[170:173], v[228:231], v[2:5]
	v_mfma_f32_16x16x32_bf16 v[54:57], v[166:169], v[186:189], v[54:57]
	v_mfma_f32_16x16x32_bf16 v[50:53], v[174:177], v[186:189], v[50:53]
	v_mfma_f32_16x16x32_bf16 v[38:41], v[166:169], v[216:219], v[38:41]
	v_mfma_f32_16x16x32_bf16 v[34:37], v[174:177], v[216:219], v[34:37]
	v_mfma_f32_16x16x32_bf16 v[22:25], v[166:169], v[224:227], v[22:25]
	v_mfma_f32_16x16x32_bf16 v[18:21], v[174:177], v[224:227], v[18:21]
	v_mfma_f32_16x16x32_bf16 v[6:9], v[166:169], v[236:239], v[6:9]
	v_mfma_f32_16x16x32_bf16 v[2:5], v[174:177], v[236:239], v[2:5]
	s_barrier
; #define PG8_STAGE(bufoff, gbase, voff) do { _Pragma("unroll") for (int _i = 0; _i < 2; ++_i) \
;         __builtin_amdgcn_global_load_lds((const unsigned*)((const char*)(gbase) + (voff)[_i]), (LAS unsigned*)(lds + (bufoff) + ldsw + _i * 8192), 16, 0, 0); } while (0)
; #define PG8_LDA(dst, b, h) do { _Pragma("unroll") for (int m = 0; m < 4; ++m) _Pragma("unroll") for (int k = 0; k < 2; ++k) dst[m][k] = *(const LAS bf16x8*)(lds + PG8_SA(b, h) + aoff + m * 2048 + k * 1024); } while (0)
; #define PG8_LDB(dst, b, h) do { _Pragma("unroll") for (int n = 0; n < 2; ++n) _Pragma("unroll") for (int k = 0; k < 2; ++k) dst[n][k] = *(const LAS bf16x8*)(lds + PG8_SB(b, h) + boff + n * 2048 + k * 1024); } while (0)
; #define PG8_MMA(ai, bj, At, Bt) do { __builtin_amdgcn_s_setprio(1); _Pragma("unroll") for (int m = 0; m < 4; ++m) _Pragma("unroll") for (int n = 0; n < 2; ++n) _Pragma("unroll") for (int k = 0; k < 2; ++k) \
;         acc[ai][bj][m][n] = __builtin_amdgcn_mfma_f32_16x16x32_bf16(Bt[n][k], At[m][k], acc[ai][bj][m][n], 0, 0, 0); __builtin_amdgcn_s_setprio(0); } while (0)
; #define PG8_WAIT_V(n) asm volatile("s_waitcnt vmcnt(" #n ")" ::: "memory")
; #define PG8_WAIT_L(n) asm volatile("s_waitcnt lgkmcnt(" #n ")" ::: "memory")
; #define PG8_BAR __builtin_amdgcn_s_barrier()
; #define PG8_SCHED __builtin_amdgcn_sched_barrier(0)
; __device__ __forceinline__ void gemm_phase(LAS unsigned char* lds, const GemmD g, const Sched& S, const Epi& E) {
;     ...
;             PG8_LDB(B0, 1, 0); PG8_LDB(B1, 1, 1); PG8_SCHED; PG8_LDA(At, 1, 0); PG8_STAGE(PG8_SA(0, 1), a2 + hstepA, voffA);
;             PG8_WAIT_V(8); PG8_WAIT_L(0); PG8_BAR; PG8_MMA(0, 0, At, B0); PG8_MMA(0, 1, At, B1); PG8_BAR; PG8_SCHED;
;             PG8_LDA(At, 1, 1); PG8_STAGE(PG8_SB(1, 0), b3, voffB); PG8_STAGE(PG8_SB(1, 1), b3 + hstepB, voffB); PG8_STAGE(PG8_SA(1, 0), a3, voffA);
;             PG8_WAIT_V(8); PG8_WAIT_L(0); PG8_BAR; PG8_MMA(1, 0, At, B0); PG8_MMA(1, 1, At, B1); PG8_BAR; PG8_SCHED;
;         }
	s_add_i32 s22, 0, 0x18000
	v_add_u32_e32 v0, s22, v160
	s_add_i32 s23, 0, 0x1c000
	ds_read_b128 v[130:133], v0
	ds_read_b128 v[146:149], v0 offset:1024
	ds_read_b128 v[150:153], v0 offset:2048
	ds_read_b128 v[154:157], v0 offset:3072
	v_add_u32_e32 v0, s23, v160
	ds_read_b128 v[162:165], v0
	ds_read_b128 v[166:169], v0 offset:1024
	ds_read_b128 v[170:173], v0 offset:2048
	ds_read_b128 v[174:177], v0 offset:3072
	s_mov_b32 m0, s15
	ds_read_b128 v[182:185], v161 offset:32768
	ds_read_b128 v[186:189], v161 offset:33792
	ds_read_b128 v[190:193], v161 offset:34816
	ds_read_b128 v[216:219], v161 offset:35840
	ds_read_b128 v[220:223], v161 offset:36864
	ds_read_b128 v[224:227], v161 offset:37888
	ds_read_b128 v[228:231], v161 offset:38912
	ds_read_b128 v[236:239], v161 offset:39936
	global_load_lds_dwordx4 v142, s[26:27]
	s_mov_b32 m0, s10
	s_nop 0
	global_load_lds_dwordx4 v144, s[26:27]
	s_waitcnt vmcnt(8)
	s_waitcnt lgkmcnt(0)
	s_barrier
	s_waitcnt lgkmcnt(0)
	v_mfma_f32_16x16x32_bf16 v[126:129], v[130:133], v[182:185], v[126:129]
	v_mfma_f32_16x16x32_bf16 v[122:125], v[150:153], v[182:185], v[122:125]
	v_mfma_f32_16x16x32_bf16 v[110:113], v[130:133], v[190:193], v[110:113]
	v_mfma_f32_16x16x32_bf16 v[106:109], v[150:153], v[190:193], v[106:109]
	v_mfma_f32_16x16x32_bf16 v[94:97], v[130:133], v[220:223], v[94:97]
	v_mfma_f32_16x16x32_bf16 v[90:93], v[150:153], v[220:223], v[90:93]
	v_mfma_f32_16x16x32_bf16 v[78:81], v[130:133], v[228:231], v[78:81]
	v_mfma_f32_16x16x32_bf16 v[74:77], v[150:153], v[228:231], v[74:77]
	v_mfma_f32_16x16x32_bf16 v[126:129], v[146:149], v[186:189], v[126:129]
	v_mfma_f32_16x16x32_bf16 v[122:125], v[154:157], v[186:189], v[122:125]
	v_mfma_f32_16x16x32_bf16 v[110:113], v[146:149], v[216:219], v[110:113]
	v_mfma_f32_16x16x32_bf16 v[106:109], v[154:157], v[216:219], v[106:109]
	v_mfma_f32_16x16x32_bf16 v[94:97], v[146:149], v[224:227], v[94:97]
	v_mfma_f32_16x16x32_bf16 v[90:93], v[154:157], v[224:227], v[90:93]
	v_mfma_f32_16x16x32_bf16 v[78:81], v[146:149], v[236:239], v[78:81]
	v_mfma_f32_16x16x32_bf16 v[74:77], v[154:157], v[236:239], v[74:77]
	v_mfma_f32_16x16x32_bf16 v[118:121], v[162:165], v[182:185], v[118:121]
	v_mfma_f32_16x16x32_bf16 v[114:117], v[170:173], v[182:185], v[114:117]
	v_mfma_f32_16x16x32_bf16 v[102:105], v[162:165], v[190:193], v[102:105]
	v_mfma_f32_16x16x32_bf16 v[98:101], v[170:173], v[190:193], v[98:101]
	v_mfma_f32_16x16x32_bf16 v[86:89], v[162:165], v[220:223], v[86:89]
	v_mfma_f32_16x16x32_bf16 v[82:85], v[170:173], v[220:223], v[82:85]
	v_mfma_f32_16x16x32_bf16 v[70:73], v[162:165], v[228:231], v[70:73]
	v_mfma_f32_16x16x32_bf16 v[66:69], v[170:173], v[228:231], v[66:69]
	v_mfma_f32_16x16x32_bf16 v[118:121], v[166:169], v[186:189], v[118:121]
	v_mfma_f32_16x16x32_bf16 v[114:117], v[174:177], v[186:189], v[114:117]
	v_mfma_f32_16x16x32_bf16 v[102:105], v[166:169], v[216:219], v[102:105]
	v_mfma_f32_16x16x32_bf16 v[98:101], v[174:177], v[216:219], v[98:101]
	v_mfma_f32_16x16x32_bf16 v[86:89], v[166:169], v[224:227], v[86:89]
	v_mfma_f32_16x16x32_bf16 v[82:85], v[174:177], v[224:227], v[82:85]
	v_mfma_f32_16x16x32_bf16 v[70:73], v[166:169], v[236:239], v[70:73]
	v_mfma_f32_16x16x32_bf16 v[66:69], v[174:177], v[236:239], v[66:69]
	s_barrier
	s_add_i32 s22, s22, s30
	s_add_u32 vcc_lo, vcc_lo, s84
	s_addc_u32 vcc_hi, vcc_hi, s85
	s_add_u32 s26, s26, s84
	s_addc_u32 s27, s27, s85
	s_mov_b32 m0, s22
	ds_read_b128 v[182:185], v161 offset:49152
	ds_read_b128 v[186:189], v161 offset:50176
	ds_read_b128 v[190:193], v161 offset:51200
	ds_read_b128 v[216:219], v161 offset:52224
	ds_read_b128 v[220:223], v161 offset:53248
	ds_read_b128 v[224:227], v161 offset:54272
	ds_read_b128 v[228:231], v161 offset:55296
	ds_read_b128 v[236:239], v161 offset:56320
	global_load_lds_dwordx4 v136, vcc
	s_add_i32 m0, s22, 0x2000
	s_add_i32 s22, s23, s30
	global_load_lds_dwordx4 v140, vcc
	s_mov_b32 m0, s22
	s_nop 0
	global_load_lds_dwordx4 v253, vcc
	s_add_i32 m0, s22, 0x2000
	s_nop 0
	global_load_lds_dwordx4 v254, vcc
	s_mov_b32 m0, s18
	s_nop 0
	global_load_lds_dwordx4 v134, s[26:27]
	s_mov_b32 m0, s19
	s_nop 0
	global_load_lds_dwordx4 v138, s[26:27]
	s_waitcnt vmcnt(8)
	s_waitcnt lgkmcnt(0)
	s_barrier
	s_waitcnt lgkmcnt(0)
	v_mfma_f32_16x16x32_bf16 v[62:65], v[130:133], v[182:185], v[62:65]
	v_mfma_f32_16x16x32_bf16 v[58:61], v[150:153], v[182:185], v[58:61]
	v_mfma_f32_16x16x32_bf16 v[46:49], v[130:133], v[190:193], v[46:49]
	v_mfma_f32_16x16x32_bf16 v[42:45], v[150:153], v[190:193], v[42:45]
	v_mfma_f32_16x16x32_bf16 v[30:33], v[130:133], v[220:223], v[30:33]
	v_mfma_f32_16x16x32_bf16 v[26:29], v[150:153], v[220:223], v[26:29]
	v_mfma_f32_16x16x32_bf16 v[14:17], v[130:133], v[228:231], v[14:17]
	v_mfma_f32_16x16x32_bf16 v[10:13], v[150:153], v[228:231], v[10:13]
	v_mfma_f32_16x16x32_bf16 v[62:65], v[146:149], v[186:189], v[62:65]
	v_mfma_f32_16x16x32_bf16 v[58:61], v[154:157], v[186:189], v[58:61]
	v_mfma_f32_16x16x32_bf16 v[46:49], v[146:149], v[216:219], v[46:49]
	v_mfma_f32_16x16x32_bf16 v[42:45], v[154:157], v[216:219], v[42:45]
	v_mfma_f32_16x16x32_bf16 v[30:33], v[146:149], v[224:227], v[30:33]
	v_mfma_f32_16x16x32_bf16 v[26:29], v[154:157], v[224:227], v[26:29]
	v_mfma_f32_16x16x32_bf16 v[14:17], v[146:149], v[236:239], v[14:17]
	v_mfma_f32_16x16x32_bf16 v[10:13], v[154:157], v[236:239], v[10:13]
	v_mfma_f32_16x16x32_bf16 v[54:57], v[162:165], v[182:185], v[54:57]
	v_mfma_f32_16x16x32_bf16 v[50:53], v[170:173], v[182:185], v[50:53]
	v_mfma_f32_16x16x32_bf16 v[38:41], v[162:165], v[190:193], v[38:41]
	v_mfma_f32_16x16x32_bf16 v[34:37], v[170:173], v[190:193], v[34:37]
	v_mfma_f32_16x16x32_bf16 v[22:25], v[162:165], v[220:223], v[22:25]
	v_mfma_f32_16x16x32_bf16 v[18:21], v[170:173], v[220:223], v[18:21]
	v_mfma_f32_16x16x32_bf16 v[6:9], v[162:165], v[228:231], v[6:9]
	v_mfma_f32_16x16x32_bf16 v[2:5], v[170:173], v[228:231], v[2:5]
	v_mfma_f32_16x16x32_bf16 v[54:57], v[166:169], v[186:189], v[54:57]
	v_mfma_f32_16x16x32_bf16 v[50:53], v[174:177], v[186:189], v[50:53]
	v_mfma_f32_16x16x32_bf16 v[38:41], v[166:169], v[216:219], v[38:41]
	v_mfma_f32_16x16x32_bf16 v[34:37], v[174:177], v[216:219], v[34:37]
	v_mfma_f32_16x16x32_bf16 v[22:25], v[166:169], v[224:227], v[22:25]
	v_mfma_f32_16x16x32_bf16 v[18:21], v[174:177], v[224:227], v[18:21]
	v_mfma_f32_16x16x32_bf16 v[6:9], v[166:169], v[236:239], v[6:9]
	v_mfma_f32_16x16x32_bf16 v[2:5], v[174:177], v[236:239], v[2:5]
	s_barrier
	s_add_u32 s8, s8, 0x100
	s_addc_u32 s9, s9, 0
	s_add_u32 s34, s34, 0x100
	s_addc_u32 s35, s35, 0
	s_cmp_ge_u32 s92, s12
	s_mov_b32 s26, s92
	s_cbranch_scc0 .LBB0_215
	s_setprio 0
	v_readlane_b32 s8, v250, 24
	v_readlane_b32 s9, v250, 25
	s_and_b64 vcc, exec, s[8:9]
	s_cbranch_vccz .LBB0_219
	s_barrier
	s_cmp_lt_i32 s96, 4
	s_mov_b64 s[8:9], -1
	s_cbranch_scc0 .LBB0_220

; template <bool COOP>
; __global__ void __launch_bounds__(512, 2) fwd_kernel(Params p) {
;     ...
;     }
; }
.LBB0_641:
	s_nop 0
	s_nop 0
	s_nop 0
	s_nop 0
	s_nop 0
	s_nop 0
	s_nop 0
	s_nop 0
	s_nop 0
	s_nop 0
	s_nop 0
	s_nop 0
	s_nop 0
	s_nop 0
	s_nop 0
	s_nop 0
	s_nop 0
	s_nop 0
	s_nop 0
	s_nop 0
	s_nop 0
	s_nop 0
	s_nop 0
	s_nop 0
	s_nop 0
	s_nop 0
	s_nop 0
	s_nop 0
	s_nop 0
	s_nop 0
	s_nop 0
	s_nop 0
	s_nop 0
	s_nop 0
	s_nop 0
	s_nop 0
	s_nop 0
	s_nop 0
	s_endpgm

; template <bool COOP>
; __global__ void __launch_bounds__(512, 2) fwd_kernel(Params p) {
	.amdhsa_kernel _Z10fwd_kernelILb1EEv6Params
		.amdhsa_group_segment_fixed_size 0
		.amdhsa_private_segment_fixed_size 0
		.amdhsa_kernarg_size 456
		.amdhsa_user_sgpr_count 2
		.amdhsa_user_sgpr_dispatch_ptr 0
		.amdhsa_user_sgpr_queue_ptr 0
		.amdhsa_user_sgpr_kernarg_segment_ptr 1
		.amdhsa_user_sgpr_dispatch_id 0
		.amdhsa_user_sgpr_kernarg_preload_length 0
		.amdhsa_user_sgpr_kernarg_preload_offset 0
		.amdhsa_user_sgpr_private_segment_size 0
		.amdhsa_uses_dynamic_stack 0
		.amdhsa_enable_private_segment 0
		.amdhsa_system_sgpr_workgroup_id_x 1
		.amdhsa_system_sgpr_workgroup_id_y 0
		.amdhsa_system_sgpr_workgroup_id_z 0
		.amdhsa_system_sgpr_workgroup_info 0
		.amdhsa_system_vgpr_workitem_id 2
		.amdhsa_next_free_vgpr 256
		.amdhsa_next_free_sgpr 100
		.amdhsa_accum_offset 256
		.amdhsa_reserve_vcc 1
		.amdhsa_float_round_mode_32 0
		.amdhsa_float_round_mode_16_64 0
		.amdhsa_float_denorm_mode_32 3
		.amdhsa_float_denorm_mode_16_64 3
		.amdhsa_dx10_clamp 1
		.amdhsa_ieee_mode 1
		.amdhsa_fp16_overflow 0
		.amdhsa_tg_split 0
		.amdhsa_exception_fp_ieee_invalid_op 0
		.amdhsa_exception_fp_denorm_src 0
		.amdhsa_exception_fp_ieee_div_zero 0
		.amdhsa_exception_fp_ieee_overflow 0
		.amdhsa_exception_fp_ieee_underflow 0
		.amdhsa_exception_fp_ieee_inexact 0
		.amdhsa_exception_int_div_zero 0
	.end_amdhsa_kernel

; template <bool COOP>
; __global__ void __launch_bounds__(512, 2) fwd_kernel(Params p) {
amdhsa.kernels:
  - .agpr_count:     0
    .args:
      - .offset:         0
        .size:           200
        .value_kind:     by_value
      - .offset:         200
        .size:           4
        .value_kind:     hidden_block_count_x
      - .offset:         204
        .size:           4
        .value_kind:     hidden_block_count_y
      - .offset:         208
        .size:           4
        .value_kind:     hidden_block_count_z
      - .offset:         212
        .size:           2
        .value_kind:     hidden_group_size_x
      - .offset:         214
        .size:           2
        .value_kind:     hidden_group_size_y
      - .offset:         216
        .size:           2
        .value_kind:     hidden_group_size_z
      - .offset:         218
        .size:           2
        .value_kind:     hidden_remainder_x
      - .offset:         220
        .size:           2
        .value_kind:     hidden_remainder_y
      - .offset:         222
        .size:           2
        .value_kind:     hidden_remainder_z
      - .offset:         240
        .size:           8
        .value_kind:     hidden_global_offset_x
      - .offset:         248
        .size:           8
        .value_kind:     hidden_global_offset_y
      - .offset:         256
        .size:           8
        .value_kind:     hidden_global_offset_z
      - .offset:         264
        .size:           2
        .value_kind:     hidden_grid_dims
      - .offset:         288
        .size:           8
        .value_kind:     hidden_multigrid_sync_arg
      - .offset:         320
        .size:           4
        .value_kind:     hidden_dynamic_lds_size
    .group_segment_fixed_size: 0
    .kernarg_segment_align: 8
    .kernarg_segment_size: 456
    .language:       OpenCL C
    .language_version:
      - 2
      - 0
    .max_flat_workgroup_size: 512
    .name:           _Z10fwd_kernelILb1EEv6Params
    .private_segment_fixed_size: 0
    .sgpr_count:     106
    .sgpr_spill_count: 227
    .symbol:         _Z10fwd_kernelILb1EEv6Params.kd
    .uniform_work_group_size: 1
    .uses_dynamic_stack: false
    .vgpr_count:     256
    .vgpr_spill_count: 0
    .wavefront_size: 64
  - .agpr_count:     0
    .args:
      - .offset:         0
        .size:           200
        .value_kind:     by_value
      - .offset:         200
        .size:           4
        .value_kind:     hidden_block_count_x
      - .offset:         204
        .size:           4
        .value_kind:     hidden_block_count_y
      - .offset:         208
        .size:           4
        .value_kind:     hidden_block_count_z
      - .offset:         212
        .size:           2
        .value_kind:     hidden_group_size_x
      - .offset:         214
        .size:           2
        .value_kind:     hidden_group_size_y
      - .offset:         216
        .size:           2
        .value_kind:     hidden_group_size_z
      - .offset:         218
        .size:           2
        .value_kind:     hidden_remainder_x
      - .offset:         220
        .size:           2
        .value_kind:     hidden_remainder_y
      - .offset:         222
        .size:           2
        .value_kind:     hidden_remainder_z
      - .offset:         240
        .size:           8
        .value_kind:     hidden_global_offset_x
      - .offset:         248
        .size:           8
        .value_kind:     hidden_global_offset_y
      - .offset:         256
        .size:           8
        .value_kind:     hidden_global_offset_z
      - .offset:         264
        .size:           2
        .value_kind:     hidden_grid_dims
      - .offset:         320
        .size:           4
        .value_kind:     hidden_dynamic_lds_size
    .group_segment_fixed_size: 0
    .kernarg_segment_align: 8
    .kernarg_segment_size: 456
    .language:       OpenCL C
    .language_version:
      - 2
      - 0
    .max_flat_workgroup_size: 512
    .name:           _Z10fwd_kernelILb0EEv6Params
    .private_segment_fixed_size: 0
    .sgpr_count:     106
    .sgpr_spill_count: 156
    .symbol:         _Z10fwd_kernelILb0EEv6Params.kd
    .uniform_work_group_size: 1
    .uses_dynamic_stack: false
    .vgpr_count:     256
    .vgpr_spill_count: 0
    .wavefront_size: 64
